# v22 + nt hint on the final y stores of P7
# speedup vs baseline: 1.0478x; 1.0081x over previous
; __device__ __forceinline__ float rstd_of(float ss) { return __builtin_amdgcn_rsqf(ss * (1.0f / DM) + EPS); }
; __device__ __forceinline__ float atomic_read_f32(float* p) { return __hip_atomic_fetch_add(p, 0.0f, __ATOMIC_RELAXED, __HIP_MEMORY_SCOPE_AGENT); }
; __device__ __forceinline__ void down_sample_tile(Frame& F, int tile, float* SS2, unsigned* cntb, float* YO) {
;     ...
;     float s = 0.f; if ((F.tid & 7) == 0) s = atomic_read_f32(SS2 + row);
;     const float rs = rstd_of(__shfl(s, F.lane & ~7));
;     *(f32x4v*)(YO + off) = (f32x4v){x0[0] * rs * ga[0], x0[1] * rs * ga[1], x0[2] * rs * ga[2], x0[3] * rs * ga[3]};
;     *(f32x4v*)(YO + off + 4) = (f32x4v){x1[0] * rs * gb[0], x1[1] * rs * gb[1], x1[2] * rs * gb[2], x1[3] * rs * gb[3]};
.LBB0_1044:
	s_or_b64 exec, exec, s[8:9]
	v_and_or_b32 v20, v0, 56, v22
	v_lshlrev_b32_e32 v20, 2, v20
	s_waitcnt vmcnt(0)
	ds_bpermute_b32 v20, v20, v23
	v_mov_b32_e32 v21, 0x358637bd
	v_lshl_add_u64 v[10:11], v[10:11], 2, s[48:49]
	v_mov_b32_e32 v139, v70
	v_mov_b32_e32 v155, v1
	s_waitcnt lgkmcnt(0)
	v_fmac_f32_e32 v21, 0x3a800000, v20
	v_rsq_f32_e32 v20, v21
	s_nop 0
	v_pk_mul_f32 v[12:13], v[12:13], v[20:21] op_sel_hi:[1,0]
	v_pk_mul_f32 v[16:17], v[16:17], v[20:21] op_sel_hi:[1,0]
	v_pk_mul_f32 v[14:15], v[14:15], v[20:21] op_sel_hi:[1,0]
	v_pk_mul_f32 v[18:19], v[18:19], v[20:21] op_sel_hi:[1,0]
	v_pk_mul_f32 v[8:9], v[8:9], v[16:17]
	v_pk_mul_f32 v[6:7], v[6:7], v[12:13]
	v_pk_mul_f32 v[4:5], v[4:5], v[18:19]
	v_pk_mul_f32 v[2:3], v[2:3], v[14:15]
	global_store_dwordx4 v[10:11], v[6:9], off nt
	global_store_dwordx4 v[10:11], v[2:5], off offset:16 nt
	s_barrier

; __device__ __forceinline__ float rstd_of(float ss) { return __builtin_amdgcn_rsqf(ss * (1.0f / DM) + EPS); }
; __device__ __forceinline__ float atomic_read_f32(float* p) { return __hip_atomic_fetch_add(p, 0.0f, __ATOMIC_RELAXED, __HIP_MEMORY_SCOPE_AGENT); }
;     __device__ __forceinline__ void operator()(pg8::f32x4 (&acc)[2][2][4][2], const Unit& u, int wr, int wc, int fr, int fq) const {
;     ...
;         pg8::f32x4 gn[2];
; #pragma unroll
;         for (int bj = 0; bj < 2; ++bj) gn[bj] = *(const pg8::f32x4*)(gain + cbase + bj * HALF);
; #pragma unroll
;         for (int ai = 0; ai < 2; ++ai)
; #pragma unroll
;             for (int m = 0; m < 4; ++m)
; #pragma unroll
;                 for (int p = 0; p < 2; ++p) { const int row = row0 + ai * HALF + m * 16 + 8 * p + rr; float s = 0.f; if (sl == 0) s = atomic_read_f32(SS2 + row); const float rs = rstd_of(__shfl(s, lane & ~7));
; #pragma unroll
;                     for (int bj = 0; bj < 2; ++bj) *(pg8::f32x4*)(YO + (size_t)row * DM + cbase + bj * HALF) = acc[ai][bj][m][p] * rs * gn[bj]; }
.LBB0_1101:
	v_readlane_b32 s64, v238, 29
	v_readlane_b32 s78, v238, 43
	v_readlane_b32 s79, v238, 44
	v_mov_b32_e32 v176, 0
	v_mov_b32_e32 v177, 0
	v_lshl_add_u64 v[2:3], v[150:151], 2, s[78:79]
	global_load_dwordx4 v[6:9], v[2:3], off
	s_waitcnt lgkmcnt(0)
	global_load_dwordx4 v[2:5], v[2:3], off offset:512
	v_readlane_b32 s65, v238, 30
	v_readlane_b32 s66, v238, 31
	v_readlane_b32 s67, v238, 32
	v_readlane_b32 s68, v238, 33
	v_readlane_b32 s69, v238, 34
	v_readlane_b32 s70, v238, 35
	v_readlane_b32 s71, v238, 36
	v_readlane_b32 s72, v238, 37
	v_readlane_b32 s73, v238, 38
	v_readlane_b32 s74, v238, 39
	v_readlane_b32 s75, v238, 40
	v_readlane_b32 s76, v238, 41
	v_readlane_b32 s77, v238, 42
	v_lshl_add_u64 v[228:229], v[152:153], 2, s[14:15]
	global_load_dword v194, v[228:229], off sc1
	global_load_dword v195, v[228:229], off offset:32 sc1
	global_load_dword v196, v[228:229], off offset:64 sc1
	global_load_dword v197, v[228:229], off offset:96 sc1
	global_load_dword v198, v[228:229], off offset:128 sc1
	global_load_dword v199, v[228:229], off offset:160 sc1
	global_load_dword v200, v[228:229], off offset:192 sc1
	global_load_dword v201, v[228:229], off offset:224 sc1
	global_load_dword v202, v[228:229], off offset:512 sc1
	global_load_dword v203, v[228:229], off offset:544 sc1
	global_load_dword v204, v[228:229], off offset:576 sc1
	global_load_dword v205, v[228:229], off offset:608 sc1
	global_load_dword v206, v[228:229], off offset:640 sc1
	global_load_dword v207, v[228:229], off offset:672 sc1
	global_load_dword v208, v[228:229], off offset:704 sc1
	global_load_dword v209, v[228:229], off offset:736 sc1
	s_waitcnt vmcnt(15)
	v_mov_b32_e32 v177, v194
	v_lshlrev_b64 v[180:181], 12, v[152:153]
	v_lshl_add_u64 v[180:181], s[48:49], 0, v[180:181]
	v_lshl_add_u64 v[180:181], v[150:151], 2, v[180:181]
	s_waitcnt lgkmcnt(0)
	v_fmamk_f32 v177, v177, 0x3a800000, v172
	v_rsq_f32_e32 v178, v177
	s_nop 0
	v_pk_mul_f32 v[128:129], v[128:129], v[178:179] op_sel_hi:[1,0]
	v_pk_mul_f32 v[124:125], v[124:125], v[178:179] op_sel_hi:[1,0]
	v_pk_mul_f32 v[126:127], v[126:127], v[178:179] op_sel_hi:[1,0]
	v_pk_mul_f32 v[178:179], v[122:123], v[178:179] op_sel_hi:[1,0]
	v_pk_mul_f32 v[124:125], v[8:9], v[124:125]
	v_pk_mul_f32 v[122:123], v[6:7], v[128:129]
	global_store_dwordx4 v[180:181], v[122:125], off nt
	s_nop 1
	v_pk_mul_f32 v[124:125], v[4:5], v[178:179]
	v_pk_mul_f32 v[122:123], v[2:3], v[126:127]
	global_store_dwordx4 v[180:181], v[122:125], off offset:512 nt
	s_nop 0
	s_waitcnt vmcnt(16)
	v_mov_b32_e32 v122, v195
	v_lshlrev_b64 v[124:125], 12, v[156:157]
	v_lshl_add_u64 v[124:125], s[48:49], 0, v[124:125]
	v_lshl_add_u64 v[124:125], v[150:151], 2, v[124:125]
	s_waitcnt lgkmcnt(0)
	v_fmamk_f32 v122, v122, 0x3a800000, v172
	v_rsq_f32_e32 v122, v122
	s_nop 0
	v_pk_mul_f32 v[116:117], v[116:117], v[122:123] op_sel_hi:[1,0]
	v_pk_mul_f32 v[118:119], v[118:119], v[122:123] op_sel_hi:[1,0]
	v_pk_mul_f32 v[126:127], v[114:115], v[122:123] op_sel_hi:[1,0]
	v_pk_mul_f32 v[120:121], v[120:121], v[122:123] op_sel_hi:[1,0]
	v_pk_mul_f32 v[116:117], v[8:9], v[116:117]
	v_pk_mul_f32 v[114:115], v[6:7], v[118:119]
	global_store_dwordx4 v[124:125], v[114:117], off nt
	s_nop 1
	v_pk_mul_f32 v[116:117], v[4:5], v[126:127]
	v_pk_mul_f32 v[114:115], v[2:3], v[120:121]
	global_store_dwordx4 v[124:125], v[114:117], off offset:512 nt
	s_nop 1
	v_or_b32_e32 v114, 16, v152
	v_ashrrev_i32_e32 v115, 31, v114
	v_mov_b32_e32 v116, 0
	v_mov_b32_e32 v117, 0
	s_nop 0
	s_waitcnt vmcnt(17)
	v_mov_b32_e32 v117, v196
	v_lshlrev_b64 v[114:115], 12, v[114:115]
	v_lshl_add_u64 v[114:115], s[48:49], 0, v[114:115]
	v_lshl_add_u64 v[114:115], v[150:151], 2, v[114:115]
	s_waitcnt lgkmcnt(0)
	v_fmamk_f32 v117, v117, 0x3a800000, v172
	v_rsq_f32_e32 v118, v117
	s_nop 0
	v_pk_mul_f32 v[106:107], v[106:107], v[118:119] op_sel_hi:[1,0]
	v_pk_mul_f32 v[120:121], v[108:109], v[118:119] op_sel_hi:[1,0]
	v_pk_mul_f32 v[110:111], v[110:111], v[118:119] op_sel_hi:[1,0]
	v_pk_mul_f32 v[112:113], v[112:113], v[118:119] op_sel_hi:[1,0]
	v_pk_mul_f32 v[108:109], v[8:9], v[106:107]
	v_pk_mul_f32 v[106:107], v[6:7], v[120:121]
	global_store_dwordx4 v[114:115], v[106:109], off nt
	s_nop 1
	v_pk_mul_f32 v[108:109], v[4:5], v[110:111]
	v_pk_mul_f32 v[106:107], v[2:3], v[112:113]
	global_store_dwordx4 v[114:115], v[106:109], off offset:512 nt
	s_nop 1
	v_or_b32_e32 v106, 24, v152
	v_ashrrev_i32_e32 v107, 31, v106
	s_nop 0
	s_waitcnt vmcnt(18)
	v_mov_b32_e32 v108, v197
	v_lshlrev_b64 v[106:107], 12, v[106:107]
	v_lshl_add_u64 v[106:107], s[48:49], 0, v[106:107]
	v_lshl_add_u64 v[106:107], v[150:151], 2, v[106:107]
	s_waitcnt lgkmcnt(0)
	v_fmamk_f32 v108, v108, 0x3a800000, v172
	v_rsq_f32_e32 v108, v108
	s_nop 0
	v_pk_mul_f32 v[100:101], v[100:101], v[108:109] op_sel_hi:[1,0]
	v_pk_mul_f32 v[102:103], v[102:103], v[108:109] op_sel_hi:[1,0]
	v_pk_mul_f32 v[110:111], v[98:99], v[108:109] op_sel_hi:[1,0]
	v_pk_mul_f32 v[104:105], v[104:105], v[108:109] op_sel_hi:[1,0]
	v_pk_mul_f32 v[100:101], v[8:9], v[100:101]
	v_pk_mul_f32 v[98:99], v[6:7], v[102:103]
	global_store_dwordx4 v[106:107], v[98:101], off nt
	s_nop 1
	v_pk_mul_f32 v[100:101], v[4:5], v[110:111]
	v_pk_mul_f32 v[98:99], v[2:3], v[104:105]
	global_store_dwordx4 v[106:107], v[98:101], off offset:512 nt
	s_nop 1
	v_or_b32_e32 v98, 32, v152
	v_ashrrev_i32_e32 v99, 31, v98
	v_mov_b32_e32 v100, 0
	v_mov_b32_e32 v101, 0
	s_nop 0
	s_waitcnt vmcnt(19)
	v_mov_b32_e32 v101, v198
	v_lshlrev_b64 v[98:99], 12, v[98:99]
	v_lshl_add_u64 v[98:99], s[48:49], 0, v[98:99]
	v_lshl_add_u64 v[98:99], v[150:151], 2, v[98:99]
	s_waitcnt lgkmcnt(0)
; __device__ __forceinline__ float rstd_of(float ss) { return __builtin_amdgcn_rsqf(ss * (1.0f / DM) + EPS); }
; __device__ __forceinline__ float atomic_read_f32(float* p) { return __hip_atomic_fetch_add(p, 0.0f, __ATOMIC_RELAXED, __HIP_MEMORY_SCOPE_AGENT); }
;     __device__ __forceinline__ void operator()(pg8::f32x4 (&acc)[2][2][4][2], const Unit& u, int wr, int wc, int fr, int fq) const {
;     ...
;         for (int ai = 0; ai < 2; ++ai)
; #pragma unroll
;             for (int m = 0; m < 4; ++m)
; #pragma unroll
;                 for (int p = 0; p < 2; ++p) { const int row = row0 + ai * HALF + m * 16 + 8 * p + rr; float s = 0.f; if (sl == 0) s = atomic_read_f32(SS2 + row); const float rs = rstd_of(__shfl(s, lane & ~7));
; #pragma unroll
;                     for (int bj = 0; bj < 2; ++bj) *(pg8::f32x4*)(YO + (size_t)row * DM + cbase + bj * HALF) = acc[ai][bj][m][p] * rs * gn[bj]; }
	v_fmamk_f32 v101, v101, 0x3a800000, v172
	v_rsq_f32_e32 v102, v101
	s_nop 0
	v_pk_mul_f32 v[90:91], v[90:91], v[102:103] op_sel_hi:[1,0]
	v_pk_mul_f32 v[104:105], v[92:93], v[102:103] op_sel_hi:[1,0]
	v_pk_mul_f32 v[94:95], v[94:95], v[102:103] op_sel_hi:[1,0]
	v_pk_mul_f32 v[96:97], v[96:97], v[102:103] op_sel_hi:[1,0]
	v_pk_mul_f32 v[92:93], v[8:9], v[90:91]
	v_pk_mul_f32 v[90:91], v[6:7], v[104:105]
	global_store_dwordx4 v[98:99], v[90:93], off nt
	s_nop 1
	v_pk_mul_f32 v[92:93], v[4:5], v[94:95]
	v_pk_mul_f32 v[90:91], v[2:3], v[96:97]
	global_store_dwordx4 v[98:99], v[90:93], off offset:512 nt
	s_nop 1
	v_or_b32_e32 v90, 40, v152
	v_ashrrev_i32_e32 v91, 31, v90
	s_nop 0
	s_waitcnt vmcnt(20)
	v_mov_b32_e32 v92, v199
	v_lshlrev_b64 v[90:91], 12, v[90:91]
	v_lshl_add_u64 v[90:91], s[48:49], 0, v[90:91]
	v_lshl_add_u64 v[90:91], v[150:151], 2, v[90:91]
	s_waitcnt lgkmcnt(0)
	v_fmamk_f32 v92, v92, 0x3a800000, v172
	v_rsq_f32_e32 v92, v92
	s_nop 0
	v_pk_mul_f32 v[84:85], v[84:85], v[92:93] op_sel_hi:[1,0]
	v_pk_mul_f32 v[86:87], v[86:87], v[92:93] op_sel_hi:[1,0]
	v_pk_mul_f32 v[94:95], v[82:83], v[92:93] op_sel_hi:[1,0]
	v_pk_mul_f32 v[88:89], v[88:89], v[92:93] op_sel_hi:[1,0]
	v_pk_mul_f32 v[84:85], v[8:9], v[84:85]
	v_pk_mul_f32 v[82:83], v[6:7], v[86:87]
	global_store_dwordx4 v[90:91], v[82:85], off nt
	s_nop 1
	v_pk_mul_f32 v[84:85], v[4:5], v[94:95]
	v_pk_mul_f32 v[82:83], v[2:3], v[88:89]
	global_store_dwordx4 v[90:91], v[82:85], off offset:512 nt
	s_nop 1
	v_or_b32_e32 v82, 48, v152
	v_ashrrev_i32_e32 v83, 31, v82
	v_mov_b32_e32 v84, 0
	v_mov_b32_e32 v85, 0
	s_nop 0
	s_waitcnt vmcnt(21)
	v_mov_b32_e32 v85, v200
	v_lshlrev_b64 v[82:83], 12, v[82:83]
	v_lshl_add_u64 v[82:83], s[48:49], 0, v[82:83]
	v_lshl_add_u64 v[82:83], v[150:151], 2, v[82:83]
	s_waitcnt lgkmcnt(0)
	v_fmamk_f32 v85, v85, 0x3a800000, v172
	v_rsq_f32_e32 v86, v85
	s_nop 0
	v_pk_mul_f32 v[74:75], v[74:75], v[86:87] op_sel_hi:[1,0]
	v_pk_mul_f32 v[88:89], v[76:77], v[86:87] op_sel_hi:[1,0]
	v_pk_mul_f32 v[78:79], v[78:79], v[86:87] op_sel_hi:[1,0]
	v_pk_mul_f32 v[80:81], v[80:81], v[86:87] op_sel_hi:[1,0]
	v_pk_mul_f32 v[76:77], v[8:9], v[74:75]
	v_pk_mul_f32 v[74:75], v[6:7], v[88:89]
	global_store_dwordx4 v[82:83], v[74:77], off nt
	s_nop 1
	v_pk_mul_f32 v[76:77], v[4:5], v[78:79]
	v_pk_mul_f32 v[74:75], v[2:3], v[80:81]
	global_store_dwordx4 v[82:83], v[74:77], off offset:512 nt
	s_nop 1
	v_or_b32_e32 v74, 56, v152
	v_ashrrev_i32_e32 v75, 31, v74
	s_nop 0
	s_waitcnt vmcnt(22)
	v_mov_b32_e32 v76, v201
	v_lshlrev_b64 v[74:75], 12, v[74:75]
	v_lshl_add_u64 v[74:75], s[48:49], 0, v[74:75]
	v_lshl_add_u64 v[74:75], v[150:151], 2, v[74:75]
	s_waitcnt lgkmcnt(0)
	v_fmamk_f32 v76, v76, 0x3a800000, v172
	v_rsq_f32_e32 v76, v76
	s_nop 0
	v_pk_mul_f32 v[68:69], v[68:69], v[76:77] op_sel_hi:[1,0]
	v_pk_mul_f32 v[70:71], v[70:71], v[76:77] op_sel_hi:[1,0]
	v_pk_mul_f32 v[78:79], v[66:67], v[76:77] op_sel_hi:[1,0]
	v_pk_mul_f32 v[72:73], v[72:73], v[76:77] op_sel_hi:[1,0]
	v_pk_mul_f32 v[68:69], v[8:9], v[68:69]
	v_pk_mul_f32 v[66:67], v[6:7], v[70:71]
	global_store_dwordx4 v[74:75], v[66:69], off nt
	s_nop 1
	v_pk_mul_f32 v[68:69], v[4:5], v[78:79]
	v_pk_mul_f32 v[66:67], v[2:3], v[72:73]
	global_store_dwordx4 v[74:75], v[66:69], off offset:512 nt
	s_nop 1
	v_add_u32_e32 v66, 0x80, v152
	v_ashrrev_i32_e32 v67, 31, v66
	v_mov_b32_e32 v68, 0
	v_mov_b32_e32 v69, 0
	s_nop 0
	s_waitcnt vmcnt(23)
	v_mov_b32_e32 v69, v202
	v_lshlrev_b64 v[66:67], 12, v[66:67]
	v_lshl_add_u64 v[66:67], s[48:49], 0, v[66:67]
	v_lshl_add_u64 v[66:67], v[150:151], 2, v[66:67]
	s_waitcnt lgkmcnt(0)
	v_fmamk_f32 v69, v69, 0x3a800000, v172
	v_rsq_f32_e32 v70, v69
	s_nop 0
	v_pk_mul_f32 v[58:59], v[58:59], v[70:71] op_sel_hi:[1,0]
	v_pk_mul_f32 v[72:73], v[60:61], v[70:71] op_sel_hi:[1,0]
	v_pk_mul_f32 v[62:63], v[62:63], v[70:71] op_sel_hi:[1,0]
	v_pk_mul_f32 v[64:65], v[64:65], v[70:71] op_sel_hi:[1,0]
	v_pk_mul_f32 v[60:61], v[8:9], v[58:59]
	v_pk_mul_f32 v[58:59], v[6:7], v[72:73]
	global_store_dwordx4 v[66:67], v[58:61], off nt
	s_nop 1
	v_pk_mul_f32 v[60:61], v[4:5], v[62:63]
	v_pk_mul_f32 v[58:59], v[2:3], v[64:65]
	global_store_dwordx4 v[66:67], v[58:61], off offset:512 nt
	s_nop 1
	v_add_u32_e32 v58, 0x88, v152
	v_ashrrev_i32_e32 v59, 31, v58
	s_nop 0
	s_waitcnt vmcnt(24)
	v_mov_b32_e32 v60, v203
	v_lshlrev_b64 v[58:59], 12, v[58:59]
	v_lshl_add_u64 v[58:59], s[48:49], 0, v[58:59]
	v_lshl_add_u64 v[58:59], v[150:151], 2, v[58:59]
	s_waitcnt lgkmcnt(0)
	v_fmamk_f32 v60, v60, 0x3a800000, v172
	v_rsq_f32_e32 v60, v60
	s_nop 0
	v_pk_mul_f32 v[52:53], v[52:53], v[60:61] op_sel_hi:[1,0]
	v_pk_mul_f32 v[54:55], v[54:55], v[60:61] op_sel_hi:[1,0]
	v_pk_mul_f32 v[62:63], v[50:51], v[60:61] op_sel_hi:[1,0]
	v_pk_mul_f32 v[56:57], v[56:57], v[60:61] op_sel_hi:[1,0]
	v_pk_mul_f32 v[52:53], v[8:9], v[52:53]
	v_pk_mul_f32 v[50:51], v[6:7], v[54:55]
	global_store_dwordx4 v[58:59], v[50:53], off nt
	s_nop 1
	v_pk_mul_f32 v[52:53], v[4:5], v[62:63]
	v_pk_mul_f32 v[50:51], v[2:3], v[56:57]
	global_store_dwordx4 v[58:59], v[50:53], off offset:512 nt
	s_nop 1
	v_add_u32_e32 v50, 0x90, v152
	v_ashrrev_i32_e32 v51, 31, v50
	v_mov_b32_e32 v52, 0
	v_mov_b32_e32 v53, 0
	s_nop 0
	s_waitcnt vmcnt(25)
; #define PG8_BAR __builtin_amdgcn_s_barrier()
; __device__ __forceinline__ float rstd_of(float ss) { return __builtin_amdgcn_rsqf(ss * (1.0f / DM) + EPS); }
; __device__ __forceinline__ float atomic_read_f32(float* p) { return __hip_atomic_fetch_add(p, 0.0f, __ATOMIC_RELAXED, __HIP_MEMORY_SCOPE_AGENT); }
; template <class Epi, class Sched, bool ALIGN_EPI = false, bool SP2 = false, bool AGM = false  >
; __device__ __forceinline__ void gemm_phase(PG8_LAS unsigned char* lds, const Gemm g, const Sched& S, const Epi& E) {
;     ...
;         if (!has_next) break;
; #pragma unroll
;         for (int a = 0; a < 2; ++a)
; #pragma unroll
;             for (int b = 0; b < 2; ++b)
; #pragma unroll
;                 for (int m = 0; m < 4; ++m)
; #pragma unroll
;                     for (int n = 0; n < 2; ++n) acc[a][b][m][n] = (f32x4){0.f, 0.f, 0.f, 0.f};
;         cur = nxt; cA = nA; cB = nB; ++ui;
;         if constexpr (ALIGN_EPI) { if (wr == 1) PG8_BAR; }
;     __device__ __forceinline__ void operator()(pg8::f32x4 (&acc)[2][2][4][2], const Unit& u, int wr, int wc, int fr, int fq) const {
;     ...
;         for (int ai = 0; ai < 2; ++ai)
; #pragma unroll
;             for (int m = 0; m < 4; ++m)
; #pragma unroll
;                 for (int p = 0; p < 2; ++p) { const int row = row0 + ai * HALF + m * 16 + 8 * p + rr; float s = 0.f; if (sl == 0) s = atomic_read_f32(SS2 + row); const float rs = rstd_of(__shfl(s, lane & ~7));
; #pragma unroll
;                     for (int bj = 0; bj < 2; ++bj) *(pg8::f32x4*)(YO + (size_t)row * DM + cbase + bj * HALF) = acc[ai][bj][m][p] * rs * gn[bj]; }
	v_mov_b32_e32 v53, v204
	v_lshlrev_b64 v[50:51], 12, v[50:51]
	v_lshl_add_u64 v[50:51], s[48:49], 0, v[50:51]
	v_lshl_add_u64 v[50:51], v[150:151], 2, v[50:51]
	s_waitcnt lgkmcnt(0)
	v_fmamk_f32 v53, v53, 0x3a800000, v172
	v_rsq_f32_e32 v54, v53
	s_nop 0
	v_pk_mul_f32 v[42:43], v[42:43], v[54:55] op_sel_hi:[1,0]
	v_pk_mul_f32 v[56:57], v[44:45], v[54:55] op_sel_hi:[1,0]
	v_pk_mul_f32 v[46:47], v[46:47], v[54:55] op_sel_hi:[1,0]
	v_pk_mul_f32 v[48:49], v[48:49], v[54:55] op_sel_hi:[1,0]
	v_pk_mul_f32 v[44:45], v[8:9], v[42:43]
	v_pk_mul_f32 v[42:43], v[6:7], v[56:57]
	global_store_dwordx4 v[50:51], v[42:45], off nt
	s_nop 1
	v_pk_mul_f32 v[44:45], v[4:5], v[46:47]
	v_pk_mul_f32 v[42:43], v[2:3], v[48:49]
	global_store_dwordx4 v[50:51], v[42:45], off offset:512 nt
	s_nop 1
	v_add_u32_e32 v42, 0x98, v152
	v_ashrrev_i32_e32 v43, 31, v42
	s_nop 0
	s_waitcnt vmcnt(26)
	v_mov_b32_e32 v44, v205
	v_lshlrev_b64 v[42:43], 12, v[42:43]
	v_lshl_add_u64 v[42:43], s[48:49], 0, v[42:43]
	v_lshl_add_u64 v[42:43], v[150:151], 2, v[42:43]
	s_waitcnt lgkmcnt(0)
	v_fmamk_f32 v44, v44, 0x3a800000, v172
	v_rsq_f32_e32 v44, v44
	s_nop 0
	v_pk_mul_f32 v[36:37], v[36:37], v[44:45] op_sel_hi:[1,0]
	v_pk_mul_f32 v[38:39], v[38:39], v[44:45] op_sel_hi:[1,0]
	v_pk_mul_f32 v[46:47], v[34:35], v[44:45] op_sel_hi:[1,0]
	v_pk_mul_f32 v[40:41], v[40:41], v[44:45] op_sel_hi:[1,0]
	v_pk_mul_f32 v[36:37], v[8:9], v[36:37]
	v_pk_mul_f32 v[34:35], v[6:7], v[38:39]
	global_store_dwordx4 v[42:43], v[34:37], off nt
	s_nop 1
	v_pk_mul_f32 v[36:37], v[4:5], v[46:47]
	v_pk_mul_f32 v[34:35], v[2:3], v[40:41]
	global_store_dwordx4 v[42:43], v[34:37], off offset:512 nt
	s_nop 1
	v_add_u32_e32 v34, 0xa0, v152
	v_ashrrev_i32_e32 v35, 31, v34
	v_mov_b32_e32 v36, 0
	v_mov_b32_e32 v37, 0
	s_nop 0
	s_waitcnt vmcnt(27)
	v_mov_b32_e32 v37, v206
	v_lshlrev_b64 v[34:35], 12, v[34:35]
	v_lshl_add_u64 v[34:35], s[48:49], 0, v[34:35]
	v_lshl_add_u64 v[34:35], v[150:151], 2, v[34:35]
	s_waitcnt lgkmcnt(0)
	v_fmamk_f32 v37, v37, 0x3a800000, v172
	v_rsq_f32_e32 v38, v37
	s_nop 0
	v_pk_mul_f32 v[26:27], v[26:27], v[38:39] op_sel_hi:[1,0]
	v_pk_mul_f32 v[40:41], v[28:29], v[38:39] op_sel_hi:[1,0]
	v_pk_mul_f32 v[30:31], v[30:31], v[38:39] op_sel_hi:[1,0]
	v_pk_mul_f32 v[32:33], v[32:33], v[38:39] op_sel_hi:[1,0]
	v_pk_mul_f32 v[28:29], v[8:9], v[26:27]
	v_pk_mul_f32 v[26:27], v[6:7], v[40:41]
	global_store_dwordx4 v[34:35], v[26:29], off nt
	s_nop 1
	v_pk_mul_f32 v[28:29], v[4:5], v[30:31]
	v_pk_mul_f32 v[26:27], v[2:3], v[32:33]
	global_store_dwordx4 v[34:35], v[26:29], off offset:512 nt
	s_nop 1
	v_add_u32_e32 v26, 0xa8, v152
	v_ashrrev_i32_e32 v27, 31, v26
	s_nop 0
	s_waitcnt vmcnt(28)
	v_mov_b32_e32 v28, v207
	v_lshlrev_b64 v[26:27], 12, v[26:27]
	v_lshl_add_u64 v[26:27], s[48:49], 0, v[26:27]
	v_lshl_add_u64 v[26:27], v[150:151], 2, v[26:27]
	s_waitcnt lgkmcnt(0)
	v_fmamk_f32 v28, v28, 0x3a800000, v172
	v_rsq_f32_e32 v28, v28
	s_nop 0
	v_pk_mul_f32 v[20:21], v[20:21], v[28:29] op_sel_hi:[1,0]
	v_pk_mul_f32 v[22:23], v[22:23], v[28:29] op_sel_hi:[1,0]
	v_pk_mul_f32 v[30:31], v[18:19], v[28:29] op_sel_hi:[1,0]
	v_pk_mul_f32 v[24:25], v[24:25], v[28:29] op_sel_hi:[1,0]
	v_pk_mul_f32 v[20:21], v[8:9], v[20:21]
	v_pk_mul_f32 v[18:19], v[6:7], v[22:23]
	global_store_dwordx4 v[26:27], v[18:21], off nt
	s_nop 1
	v_pk_mul_f32 v[20:21], v[4:5], v[30:31]
	v_pk_mul_f32 v[18:19], v[2:3], v[24:25]
	global_store_dwordx4 v[26:27], v[18:21], off offset:512 nt
	s_nop 1
	v_add_u32_e32 v18, 0xb0, v152
	v_ashrrev_i32_e32 v19, 31, v18
	v_mov_b32_e32 v20, 0
	v_mov_b32_e32 v21, 0
	s_nop 0
	s_waitcnt vmcnt(29)
	v_mov_b32_e32 v21, v208
	v_lshlrev_b64 v[18:19], 12, v[18:19]
	v_lshl_add_u64 v[18:19], s[48:49], 0, v[18:19]
	v_lshl_add_u64 v[18:19], v[150:151], 2, v[18:19]
	s_waitcnt lgkmcnt(0)
	v_fmamk_f32 v21, v21, 0x3a800000, v172
	v_rsq_f32_e32 v22, v21
	s_nop 0
	v_pk_mul_f32 v[24:25], v[158:159], v[22:23] op_sel_hi:[1,0]
	v_pk_mul_f32 v[26:27], v[160:161], v[22:23] op_sel_hi:[1,0]
	v_pk_mul_f32 v[28:29], v[162:163], v[22:23] op_sel_hi:[1,0]
	v_pk_mul_f32 v[30:31], v[164:165], v[22:23] op_sel_hi:[1,0]
	v_pk_mul_f32 v[24:25], v[8:9], v[24:25]
	v_pk_mul_f32 v[22:23], v[6:7], v[26:27]
	global_store_dwordx4 v[18:19], v[22:25], off nt
	s_nop 1
	v_pk_mul_f32 v[24:25], v[4:5], v[28:29]
	v_pk_mul_f32 v[22:23], v[2:3], v[30:31]
	global_store_dwordx4 v[18:19], v[22:25], off offset:512 nt
	v_add_u32_e32 v18, 0xb8, v152
	v_ashrrev_i32_e32 v19, 31, v18
	s_nop 0
	s_waitcnt vmcnt(30)
	v_mov_b32_e32 v20, v209
	v_lshlrev_b64 v[18:19], 12, v[18:19]
	v_lshl_add_u64 v[18:19], s[48:49], 0, v[18:19]
	v_lshl_add_u64 v[18:19], v[150:151], 2, v[18:19]
	s_and_b64 vcc, exec, s[10:11]
	s_waitcnt lgkmcnt(0)
	v_fmamk_f32 v20, v20, 0x3a800000, v172
	v_rsq_f32_e32 v20, v20
	s_mov_b64 s[4:5], -1
	v_pk_mul_f32 v[12:13], v[12:13], v[20:21] op_sel_hi:[1,0]
	v_pk_mul_f32 v[14:15], v[14:15], v[20:21] op_sel_hi:[1,0]
	v_pk_mul_f32 v[10:11], v[10:11], v[20:21] op_sel_hi:[1,0]
	v_pk_mul_f32 v[16:17], v[16:17], v[20:21] op_sel_hi:[1,0]
	v_pk_mul_f32 v[8:9], v[8:9], v[12:13]
	v_pk_mul_f32 v[6:7], v[6:7], v[14:15]
	v_pk_mul_f32 v[4:5], v[4:5], v[10:11]
	v_pk_mul_f32 v[2:3], v[2:3], v[16:17]
	global_store_dwordx4 v[18:19], v[6:9], off nt
	global_store_dwordx4 v[18:19], v[2:5], off offset:512 nt
	s_cbranch_vccnz .LBB0_1056
	s_andn2_b64 vcc, exec, s[22:23]
	s_cbranch_vccnz .LBB0_1055
	s_barrier
	s_branch .LBB0_1055

; __device__ __forceinline__ float rstd_of(float ss) { return __builtin_amdgcn_rsqf(ss * (1.0f / DM) + EPS); }
; __device__ __forceinline__ float atomic_read_f32(float* p) { return __hip_atomic_fetch_add(p, 0.0f, __ATOMIC_RELAXED, __HIP_MEMORY_SCOPE_AGENT); }
; __device__ __forceinline__ void down_sample_tile(Frame& F, int tile, float* SS2, unsigned* cntb, float* YO) {
;     ...
;     float s = 0.f; if ((F.tid & 7) == 0) s = atomic_read_f32(SS2 + row);
;     const float rs = rstd_of(__shfl(s, F.lane & ~7));
;     *(f32x4v*)(YO + off) = (f32x4v){x0[0] * rs * ga[0], x0[1] * rs * ga[1], x0[2] * rs * ga[2], x0[3] * rs * ga[3]};
;     *(f32x4v*)(YO + off + 4) = (f32x4v){x1[0] * rs * gb[0], x1[1] * rs * gb[1], x1[2] * rs * gb[2], x1[3] * rs * gb[3]};
; __global__ void __launch_bounds__(NWAVES * 64, 2) mk_fwd(Args args) {
;     ...
;         if (F.G != 256) { for (int it = F.bid; it < 256; it += F.G) down_sample_tile(F, it, (float*)(F.ws + WS_CTL) + CW_SS2, (unsigned*)(F.ws + WS_CTL) + CW_CNTS, F.out + O_Y); }
.LBB0_1140:
	s_or_b64 exec, exec, s[4:5]
	s_waitcnt vmcnt(0)
	ds_bpermute_b32 v20, v89, v22
	s_add_i32 s2, s52, s2
	v_lshl_add_u64 v[10:11], v[10:11], 2, s[48:49]
	s_cmpk_gt_i32 s2, 0xff
	s_waitcnt lgkmcnt(0)
	v_fmamk_f32 v20, v20, 0x3a800000, v93
	v_rsq_f32_e32 v20, v20
	s_nop 0
	v_pk_mul_f32 v[12:13], v[12:13], v[20:21] op_sel_hi:[1,0]
	v_pk_mul_f32 v[16:17], v[16:17], v[20:21] op_sel_hi:[1,0]
	v_pk_mul_f32 v[14:15], v[14:15], v[20:21] op_sel_hi:[1,0]
	v_pk_mul_f32 v[18:19], v[18:19], v[20:21] op_sel_hi:[1,0]
	v_pk_mul_f32 v[8:9], v[8:9], v[16:17]
	v_pk_mul_f32 v[6:7], v[6:7], v[12:13]
	v_pk_mul_f32 v[4:5], v[4:5], v[18:19]
	v_pk_mul_f32 v[2:3], v[2:3], v[14:15]
	global_store_dwordx4 v[10:11], v[6:9], off nt
	global_store_dwordx4 v[10:11], v[2:5], off offset:16 nt
	s_cbranch_scc1 .LBB0_1159

; __device__ __forceinline__ float rstd_of(float ss) { return __builtin_amdgcn_rsqf(ss * (1.0f / DM) + EPS); }
; __device__ __forceinline__ float atomic_read_f32(float* p) { return __hip_atomic_fetch_add(p, 0.0f, __ATOMIC_RELAXED, __HIP_MEMORY_SCOPE_AGENT); }
; __device__ __forceinline__ void down_sample_tile(Frame& F, int tile, float* SS2, unsigned* cntb, float* YO) {
;     ...
;     float s = 0.f; if ((F.tid & 7) == 0) s = atomic_read_f32(SS2 + row);
;     const float rs = rstd_of(__shfl(s, F.lane & ~7));
;     *(f32x4v*)(YO + off) = (f32x4v){x0[0] * rs * ga[0], x0[1] * rs * ga[1], x0[2] * rs * ga[2], x0[3] * rs * ga[3]};
;     *(f32x4v*)(YO + off + 4) = (f32x4v){x1[0] * rs * gb[0], x1[1] * rs * gb[1], x1[2] * rs * gb[2], x1[3] * rs * gb[3]};
.LBB0_1180:
	s_or_b64 exec, exec, s[2:3]
	v_and_or_b32 v0, v0, 56, v1
	v_lshlrev_b32_e32 v0, 2, v0
	s_waitcnt vmcnt(0)
	ds_bpermute_b32 v0, v0, v22
	v_mov_b32_e32 v1, 0x358637bd
	v_lshl_add_u64 v[10:11], v[10:11], 2, s[48:49]
	s_waitcnt lgkmcnt(0)
	v_fmac_f32_e32 v1, 0x3a800000, v0
	v_rsq_f32_e32 v0, v1
	s_nop 0
	v_pk_mul_f32 v[12:13], v[12:13], v[0:1] op_sel_hi:[1,0]
	v_pk_mul_f32 v[16:17], v[16:17], v[0:1] op_sel_hi:[1,0]
	v_pk_mul_f32 v[14:15], v[14:15], v[0:1] op_sel_hi:[1,0]
	v_pk_mul_f32 v[0:1], v[18:19], v[0:1] op_sel_hi:[1,0]
	v_pk_mul_f32 v[8:9], v[8:9], v[16:17]
	v_pk_mul_f32 v[6:7], v[6:7], v[12:13]
	v_pk_mul_f32 v[4:5], v[4:5], v[0:1]
	v_pk_mul_f32 v[2:3], v[2:3], v[14:15]
	global_store_dwordx4 v[10:11], v[6:9], off nt
	global_store_dwordx4 v[10:11], v[2:5], off offset:16 nt
